# moba_attn body: running-max lane^16 / lane^32 reductions with v_permlane16/32_swap instead of ds_bpermute (8 LDS round trips less per key-tile pair)
# baseline (speedup 1.0000x reference)
.LBB0_1269:
	v_mov_b32_e32 v161, v130
	v_add_u32_e32 v130, 0, v159
	ds_read_b128 v[98:101], v130
	ds_read_b128 v[102:105], v130 offset:64
	ds_read_b128 v[106:109], v130 offset:128
	ds_read_b128 v[110:113], v130 offset:192
	ds_read_b128 v[114:117], v130 offset:4352
	ds_read_b128 v[118:121], v130 offset:4416
	ds_read_b128 v[122:125], v130 offset:4480
	ds_read_b128 v[126:129], v130 offset:4544
	s_waitcnt vmcnt(3) lgkmcnt(7)
	v_mfma_f32_16x16x32_bf16 v[162:165], v[98:101], v[14:17], 0
	v_mov_b32_e32 v183, v132
	s_add_i32 s0, s0, -1
	v_add_u32_e32 v159, 0x4400, v159
	v_mfma_f32_16x16x32_bf16 v[98:101], v[98:101], v[18:21], 0
	s_cmp_lg_u32 s0, 0
	s_waitcnt lgkmcnt(6)
	v_mfma_f32_16x16x32_bf16 v[162:165], v[102:105], v[2:5], v[162:165]
	s_waitcnt vmcnt(2)
	v_mfma_f32_16x16x32_bf16 v[98:101], v[102:105], v[22:25], v[98:101]
	s_waitcnt lgkmcnt(5)
	v_mfma_f32_16x16x32_bf16 v[102:105], v[106:109], v[6:9], v[162:165]
	s_waitcnt vmcnt(1)
	v_mfma_f32_16x16x32_bf16 v[106:109], v[106:109], v[26:29], v[98:101]
	s_waitcnt lgkmcnt(4)
	v_mfma_f32_16x16x32_bf16 v[98:101], v[110:113], v[10:13], v[102:105]
	s_nop 3
	ds_read_b128 v[102:105], v130 offset:8704
	ds_read_b128 v[162:165], v130 offset:8768
	ds_read_b128 v[166:169], v130 offset:8832
	ds_read_b128 v[170:173], v130 offset:8896
	s_waitcnt vmcnt(0)
	v_mfma_f32_16x16x32_bf16 v[106:109], v[110:113], v[30:33], v[106:109]
	s_waitcnt lgkmcnt(7)
	v_mfma_f32_16x16x32_bf16 v[110:113], v[114:117], v[14:17], 0
	v_mfma_f32_16x16x32_bf16 v[114:117], v[114:117], v[18:21], 0
	s_waitcnt lgkmcnt(6)
	v_mfma_f32_16x16x32_bf16 v[110:113], v[118:121], v[2:5], v[110:113]
	v_mfma_f32_16x16x32_bf16 v[114:117], v[118:121], v[22:25], v[114:117]
	s_waitcnt lgkmcnt(5)
	v_mfma_f32_16x16x32_bf16 v[110:113], v[122:125], v[6:9], v[110:113]
	v_mfma_f32_16x16x32_bf16 v[114:117], v[122:125], v[26:29], v[114:117]
	s_waitcnt lgkmcnt(3)
	v_mfma_f32_16x16x32_bf16 v[122:125], v[102:105], v[14:17], 0
	v_mfma_f32_16x16x32_bf16 v[102:105], v[102:105], v[18:21], 0
	s_waitcnt lgkmcnt(2)
	v_mfma_f32_16x16x32_bf16 v[122:125], v[162:165], v[2:5], v[122:125]
	v_mfma_f32_16x16x32_bf16 v[102:105], v[162:165], v[22:25], v[102:105]
	s_waitcnt lgkmcnt(1)
	v_mfma_f32_16x16x32_bf16 v[122:125], v[166:169], v[6:9], v[122:125]
	v_mfma_f32_16x16x32_bf16 v[102:105], v[166:169], v[26:29], v[102:105]
	v_mfma_f32_16x16x32_bf16 v[174:177], v[126:129], v[10:13], v[110:113]
	v_mfma_f32_16x16x32_bf16 v[110:113], v[126:129], v[30:33], v[114:117]
	s_nop 2
	ds_read_b128 v[114:117], v130 offset:13056
	ds_read_b128 v[118:121], v130 offset:13120
	ds_read_b128 v[126:129], v130 offset:13184
	ds_read_b128 v[178:181], v130 offset:13248
	s_waitcnt lgkmcnt(4)
	v_mfma_f32_16x16x32_bf16 v[162:165], v[170:173], v[10:13], v[122:125]
	v_mfma_f32_16x16x32_bf16 v[122:125], v[170:173], v[30:33], v[102:105]
	s_waitcnt lgkmcnt(3)
	v_mfma_f32_16x16x32_bf16 v[102:105], v[114:117], v[14:17], 0
	v_mfma_f32_16x16x32_bf16 v[114:117], v[114:117], v[18:21], 0
	s_waitcnt lgkmcnt(2)
	v_mfma_f32_16x16x32_bf16 v[102:105], v[118:121], v[2:5], v[102:105]
	v_mfma_f32_16x16x32_bf16 v[114:117], v[118:121], v[22:25], v[114:117]
	s_waitcnt lgkmcnt(1)
	v_mfma_f32_16x16x32_bf16 v[102:105], v[126:129], v[6:9], v[102:105]
	v_mfma_f32_16x16x32_bf16 v[114:117], v[126:129], v[26:29], v[114:117]
	v_max3_f32 v126, v98, s33, v99
	v_max3_f32 v126, v126, v100, v101
	v_max3_f32 v126, v126, v174, v175
	s_waitcnt lgkmcnt(0)
	v_mfma_f32_16x16x32_bf16 v[102:105], v[178:181], v[10:13], v[102:105]
	v_max3_f32 v126, v126, v176, v177
	v_max3_f32 v126, v126, v162, v163
	v_max3_f32 v126, v126, v164, v165
	v_mfma_f32_16x16x32_bf16 v[166:169], v[178:181], v[30:33], v[114:117]
	v_add_u32_e32 v128, 0, v160
	s_nop 2
	v_max3_f32 v126, v126, v102, v103
	v_max3_f32 v126, v126, v104, v105
	v_mov_b32_e32 v127, v126
	v_mov_b32_e32 v136, v126
	s_nop 1
	v_permlane16_swap_b32_e32 v127, v136
	v_add_u32_e32 v114, 0x11800, v128
	v_add_u32_e32 v116, 0x11820, v128
	v_add_u32_e32 v118, 0x11840, v128
	v_add_u32_e32 v120, 0x11860, v128
	s_waitcnt lgkmcnt(0)
	v_max_f32_e32 v126, v127, v136
	v_mov_b32_e32 v127, v126
	v_mov_b32_e32 v136, v126
	s_nop 1
	v_permlane32_swap_b32_e32 v127, v136
	ds_read_b64 v[114:115], v114
	ds_read_b64 v[116:117], v116
	ds_read_b64 v[118:119], v118
	ds_read_b64 v[120:121], v120
	s_waitcnt lgkmcnt(4)
	v_max3_f32 v130, v161, v127, v136
	v_sub_f32_e32 v127, v161, v130
	v_exp_f32_e32 v196, v127
	v_max3_f32 v127, v106, s33, v107
	v_max3_f32 v127, v127, v108, v109
	v_max3_f32 v127, v127, v110, v111
	v_max3_f32 v127, v127, v112, v113
	v_max3_f32 v127, v127, v122, v123
	v_max3_f32 v127, v127, v124, v125
	v_max3_f32 v127, v127, v166, v167
	v_max3_f32 v127, v127, v168, v169
	v_mov_b32_e32 v129, v127
	v_mov_b32_e32 v136, v127
	s_nop 1
	v_permlane16_swap_b32_e32 v129, v136
	v_sub_f32_e32 v98, v98, v130
	v_exp_f32_e32 v126, v98
	v_sub_f32_e32 v98, v99, v130
	v_exp_f32_e32 v170, v98
	s_waitcnt lgkmcnt(0)
	v_max_f32_e32 v127, v129, v136
	v_mov_b32_e32 v129, v127
	v_mov_b32_e32 v136, v127
	s_nop 1
	v_permlane32_swap_b32_e32 v129, v136
	v_sub_f32_e32 v98, v100, v130
	v_exp_f32_e32 v172, v98
	v_sub_f32_e32 v98, v101, v130
	v_exp_f32_e32 v178, v98
	s_waitcnt lgkmcnt(0)
	v_max3_f32 v132, v183, v129, v136
	v_sub_f32_e32 v106, v106, v132
	v_exp_f32_e32 v127, v106
	v_sub_f32_e32 v106, v107, v132
	v_exp_f32_e32 v171, v106
	v_sub_f32_e32 v106, v108, v132
	v_exp_f32_e32 v173, v106
	v_sub_f32_e32 v106, v109, v132
	v_sub_f32_e32 v98, v174, v130
	v_exp_f32_e32 v179, v106
	v_sub_f32_e32 v106, v110, v132
	v_exp_f32_e32 v174, v98
	v_sub_f32_e32 v98, v175, v130
	v_exp_f32_e32 v175, v106
	v_sub_f32_e32 v106, v111, v132
	v_exp_f32_e32 v181, v106
	v_pk_add_f32 v[106:107], v[126:127], 0 op_sel_hi:[1,0]
	v_exp_f32_e32 v180, v98
	v_sub_f32_e32 v98, v176, v130
	v_pk_add_f32 v[106:107], v[170:171], v[106:107]
	v_sub_f32_e32 v108, v112, v132
	v_exp_f32_e32 v176, v98
	v_sub_f32_e32 v98, v177, v130
	v_pk_add_f32 v[106:107], v[172:173], v[106:107]
	v_exp_f32_e32 v177, v108
	v_sub_f32_e32 v108, v113, v132
	v_exp_f32_e32 v182, v98
	v_sub_f32_e32 v98, v162, v130
	v_sub_f32_e32 v129, v183, v132
	v_pk_add_f32 v[106:107], v[178:179], v[106:107]
	v_exp_f32_e32 v183, v108
	v_sub_f32_e32 v108, v122, v132
	v_exp_f32_e32 v162, v98
	v_sub_f32_e32 v98, v163, v130
	v_pk_add_f32 v[106:107], v[174:175], v[106:107]
	v_exp_f32_e32 v163, v108
	v_sub_f32_e32 v108, v123, v132
	v_exp_f32_e32 v184, v98
	v_sub_f32_e32 v98, v164, v130
	v_pk_add_f32 v[106:107], v[180:181], v[106:107]
	v_exp_f32_e32 v185, v108
	v_sub_f32_e32 v108, v124, v132
	v_exp_f32_e32 v164, v98
	v_sub_f32_e32 v98, v165, v130
	v_exp_f32_e32 v165, v108
	v_sub_f32_e32 v108, v125, v132
	v_pk_add_f32 v[106:107], v[176:177], v[106:107]
	v_exp_f32_e32 v186, v98
	v_sub_f32_e32 v98, v102, v130
	v_exp_f32_e32 v187, v108
	v_sub_f32_e32 v108, v166, v132
	v_pk_add_f32 v[106:107], v[182:183], v[106:107]
	v_exp_f32_e32 v188, v98
	v_sub_f32_e32 v98, v103, v130
	v_exp_f32_e32 v189, v108
	v_sub_f32_e32 v108, v167, v132
	v_pk_add_f32 v[106:107], v[162:163], v[106:107]
	v_exp_f32_e32 v190, v98
	v_sub_f32_e32 v98, v104, v130
	v_exp_f32_e32 v191, v108
	v_sub_f32_e32 v108, v168, v132
	v_pk_add_f32 v[106:107], v[184:185], v[106:107]
	v_exp_f32_e32 v192, v98
	v_sub_f32_e32 v98, v105, v130
	v_exp_f32_e32 v193, v108
	v_sub_f32_e32 v108, v169, v132
	v_pk_add_f32 v[106:107], v[164:165], v[106:107]
	v_exp_f32_e32 v194, v98
	v_exp_f32_e32 v195, v108
	v_pk_add_f32 v[106:107], v[186:187], v[106:107]
	v_pk_mul_f32 v[60:61], v[60:61], v[196:197] op_sel_hi:[1,0]
	v_pk_mul_f32 v[58:59], v[58:59], v[196:197] op_sel_hi:[1,0]
	v_pk_mul_f32 v[64:65], v[64:65], v[196:197] op_sel_hi:[1,0]
	v_pk_mul_f32 v[62:63], v[62:63], v[196:197] op_sel_hi:[1,0]
	v_pk_mul_f32 v[68:69], v[68:69], v[196:197] op_sel_hi:[1,0]
	v_pk_mul_f32 v[66:67], v[66:67], v[196:197] op_sel_hi:[1,0]
	v_pk_mul_f32 v[72:73], v[72:73], v[196:197] op_sel_hi:[1,0]
	v_pk_mul_f32 v[70:71], v[70:71], v[196:197] op_sel_hi:[1,0]
	v_pk_mul_f32 v[76:77], v[76:77], v[196:197] op_sel_hi:[1,0]
	v_pk_mul_f32 v[74:75], v[74:75], v[196:197] op_sel_hi:[1,0]
	v_pk_mul_f32 v[80:81], v[80:81], v[196:197] op_sel_hi:[1,0]
	v_pk_mul_f32 v[78:79], v[78:79], v[196:197] op_sel_hi:[1,0]
	v_pk_mul_f32 v[92:93], v[92:93], v[196:197] op_sel_hi:[1,0]
	v_pk_mul_f32 v[90:91], v[90:91], v[196:197] op_sel_hi:[1,0]
	v_pk_mul_f32 v[100:101], v[96:97], v[196:197] op_sel_hi:[1,0]
	v_pk_mul_f32 v[98:99], v[94:95], v[196:197] op_sel_hi:[1,0]
	v_exp_f32_e32 v197, v129
	v_pk_add_f32 v[106:107], v[188:189], v[106:107]
	v_add_u32_e32 v122, 0x13900, v128
	v_pk_add_f32 v[106:107], v[190:191], v[106:107]
	v_add_u32_e32 v124, 0x13920, v128
	v_pk_add_f32 v[106:107], v[192:193], v[106:107]
	v_cvt_pk_bf16_f32 v102, v126, v170
	v_cvt_pk_bf16_f32 v103, v172, v178
	v_cvt_pk_bf16_f32 v104, v174, v180
	v_cvt_pk_bf16_f32 v105, v176, v182
	v_cvt_pk_bf16_f32 v94, v162, v184
	s_nop 0
	v_pk_add_f32 v[106:107], v[194:195], v[106:107]
	v_cvt_pk_bf16_f32 v95, v164, v186
	v_cvt_pk_bf16_f32 v96, v188, v190
	v_cvt_pk_bf16_f32 v97, v192, v194
	v_add_u32_e32 v126, 0x13940, v128
	v_pk_fma_f32 v[150:151], v[150:151], v[196:197], v[106:107]
	v_mov_b32_e32 v106, v197
	v_pk_mul_f32 v[36:37], v[36:37], v[106:107] op_sel_hi:[1,0]
	v_pk_mul_f32 v[34:35], v[34:35], v[106:107] op_sel_hi:[1,0]
	v_pk_mul_f32 v[40:41], v[40:41], v[106:107] op_sel_hi:[1,0]
	v_pk_mul_f32 v[38:39], v[38:39], v[106:107] op_sel_hi:[1,0]
	v_pk_mul_f32 v[44:45], v[44:45], v[106:107] op_sel_hi:[1,0]
	v_pk_mul_f32 v[42:43], v[42:43], v[106:107] op_sel_hi:[1,0]
	v_pk_mul_f32 v[48:49], v[48:49], v[106:107] op_sel_hi:[1,0]
	v_pk_mul_f32 v[46:47], v[46:47], v[106:107] op_sel_hi:[1,0]
	v_pk_mul_f32 v[52:53], v[52:53], v[106:107] op_sel_hi:[1,0]
	v_pk_mul_f32 v[50:51], v[50:51], v[106:107] op_sel_hi:[1,0]
	v_pk_mul_f32 v[56:57], v[56:57], v[106:107] op_sel_hi:[1,0]
	v_pk_mul_f32 v[54:55], v[54:55], v[106:107] op_sel_hi:[1,0]
	v_pk_mul_f32 v[88:89], v[88:89], v[106:107] op_sel_hi:[1,0]
	v_pk_mul_f32 v[86:87], v[86:87], v[106:107] op_sel_hi:[1,0]
	v_pk_mul_f32 v[84:85], v[84:85], v[106:107] op_sel_hi:[1,0]
	v_pk_mul_f32 v[82:83], v[82:83], v[106:107] op_sel_hi:[1,0]
	v_cvt_pk_bf16_f32 v106, v127, v171
	v_cvt_pk_bf16_f32 v107, v173, v179
	v_cvt_pk_bf16_f32 v108, v175, v181
	v_cvt_pk_bf16_f32 v109, v177, v183
	v_cvt_pk_bf16_f32 v110, v163, v185
	v_cvt_pk_bf16_f32 v111, v165, v187
	v_cvt_pk_bf16_f32 v112, v189, v191
	v_cvt_pk_bf16_f32 v113, v193, v195
	ds_read_b64 v[122:123], v122
	ds_read_b64 v[124:125], v124
	ds_read_b64 v[162:163], v126
	v_add_u32_e32 v126, 0x13960, v128
	v_mfma_f32_16x16x32_bf16 v[58:61], v[114:117], v[102:105], v[58:61]
	ds_read_b64 v[164:165], v126
	v_add_u32_e32 v160, 0x80, v160
	v_mfma_f32_16x16x32_bf16 v[34:37], v[114:117], v[106:109], v[34:37]
	v_add_u32_e32 v114, 0x15a00, v128
	v_add_u32_e32 v116, 0x15a20, v128
	ds_read_b64 v[114:115], v114
	ds_read_b64 v[116:117], v116
	s_waitcnt lgkmcnt(4)
	v_mfma_f32_16x16x32_bf16 v[62:65], v[122:125], v[102:105], v[62:65]
	v_mfma_f32_16x16x32_bf16 v[38:41], v[122:125], v[106:109], v[38:41]
	v_add_u32_e32 v122, 0x17b00, v128
	v_add_u32_e32 v124, 0x17b20, v128
	ds_read_b64 v[122:123], v122
	ds_read_b64 v[124:125], v124
	v_mfma_f32_16x16x32_bf16 v[58:61], v[118:121], v[94:97], v[58:61]
	v_add_u32_e32 v126, 0x17b40, v128
	v_mfma_f32_16x16x32_bf16 v[34:37], v[118:121], v[110:113], v[34:37]
	v_add_u32_e32 v118, 0x15a40, v128
	v_add_u32_e32 v120, 0x15a60, v128
	ds_read_b64 v[118:119], v118
	ds_read_b64 v[120:121], v120
	s_waitcnt lgkmcnt(4)
	v_mfma_f32_16x16x32_bf16 v[66:69], v[114:117], v[102:105], v[66:69]
	v_mfma_f32_16x16x32_bf16 v[42:45], v[114:117], v[106:109], v[42:45]
	v_add_u32_e32 v114, 0x19c00, v128
	v_add_u32_e32 v116, 0x19c20, v128
	ds_read_b64 v[114:115], v114
	ds_read_b64 v[116:117], v116
	s_waitcnt lgkmcnt(4)
	v_mfma_f32_16x16x32_bf16 v[70:73], v[122:125], v[102:105], v[70:73]
	v_mfma_f32_16x16x32_bf16 v[46:49], v[122:125], v[106:109], v[46:49]
	v_add_u32_e32 v122, 0x1bd00, v128
	v_add_u32_e32 v124, 0x1bd20, v128
	ds_read_b64 v[122:123], v122
	ds_read_b64 v[124:125], v124
	v_mfma_f32_16x16x32_bf16 v[62:65], v[162:165], v[94:97], v[62:65]
	v_mfma_f32_16x16x32_bf16 v[38:41], v[162:165], v[110:113], v[38:41]
	ds_read_b64 v[162:163], v126
	v_add_u32_e32 v126, 0x17b60, v128
	ds_read_b64 v[164:165], v126
	s_waitcnt lgkmcnt(6)
	v_mfma_f32_16x16x32_bf16 v[66:69], v[118:121], v[94:97], v[66:69]
	v_mfma_f32_16x16x32_bf16 v[42:45], v[118:121], v[110:113], v[42:45]
	v_add_u32_e32 v118, 0x19c40, v128
	v_add_u32_e32 v120, 0x19c60, v128
	ds_read_b64 v[118:119], v118
	ds_read_b64 v[120:121], v120
	s_waitcnt lgkmcnt(6)
	v_mfma_f32_16x16x32_bf16 v[74:77], v[114:117], v[102:105], v[74:77]
	v_mfma_f32_16x16x32_bf16 v[50:53], v[114:117], v[106:109], v[50:53]
	v_add_u32_e32 v114, 0x1de00, v128
	v_add_u32_e32 v116, 0x1de20, v128
	ds_read_b64 v[114:115], v114
	ds_read_b64 v[116:117], v116
	s_waitcnt lgkmcnt(6)
	v_mfma_f32_16x16x32_bf16 v[78:81], v[122:125], v[102:105], v[78:81]
	v_mfma_f32_16x16x32_bf16 v[54:57], v[122:125], v[106:109], v[54:57]
	v_add_u32_e32 v122, 0x1ff00, v128
	v_add_u32_e32 v124, 0x1ff20, v128
	ds_read_b64 v[122:123], v122
	ds_read_b64 v[124:125], v124
	v_add_u32_e32 v126, 0x1bd40, v128
	s_waitcnt lgkmcnt(6)
	v_mfma_f32_16x16x32_bf16 v[70:73], v[162:165], v[94:97], v[70:73]
	v_mfma_f32_16x16x32_bf16 v[46:49], v[162:165], v[110:113], v[46:49]
	ds_read_b64 v[162:163], v126
	v_add_u32_e32 v126, 0x1bd60, v128
	ds_read_b64 v[164:165], v126
	s_waitcnt lgkmcnt(6)
	v_mfma_f32_16x16x32_bf16 v[74:77], v[118:121], v[94:97], v[74:77]
	v_add_u32_e32 v126, 0x1ff40, v128
	ds_read_b64 v[126:127], v126
	v_mfma_f32_16x16x32_bf16 v[50:53], v[118:121], v[110:113], v[50:53]
	v_add_u32_e32 v118, 0x1de40, v128
	v_add_u32_e32 v120, 0x1de60, v128
	v_add_u32_e32 v128, 0x1ff60, v128
	ds_read_b64 v[118:119], v118
	ds_read_b64 v[120:121], v120
	ds_read_b64 v[128:129], v128
	s_waitcnt lgkmcnt(8)
	v_mfma_f32_16x16x32_bf16 v[90:93], v[114:117], v[102:105], v[90:93]
	v_mfma_f32_16x16x32_bf16 v[86:89], v[114:117], v[106:109], v[86:89]
	s_waitcnt lgkmcnt(6)
	v_mfma_f32_16x16x32_bf16 v[98:101], v[122:125], v[102:105], v[98:101]
	v_mfma_f32_16x16x32_bf16 v[82:85], v[122:125], v[106:109], v[82:85]
	s_waitcnt lgkmcnt(4)
	v_mfma_f32_16x16x32_bf16 v[78:81], v[162:165], v[94:97], v[78:81]
	v_mfma_f32_16x16x32_bf16 v[54:57], v[162:165], v[110:113], v[54:57]
	s_waitcnt lgkmcnt(1)
	v_mfma_f32_16x16x32_bf16 v[90:93], v[118:121], v[94:97], v[90:93]
	v_mfma_f32_16x16x32_bf16 v[86:89], v[118:121], v[110:113], v[86:89]
	s_waitcnt lgkmcnt(0)
	v_mfma_f32_16x16x32_bf16 v[94:97], v[126:129], v[94:97], v[98:101]
	v_mfma_f32_16x16x32_bf16 v[82:85], v[126:129], v[110:113], v[82:85]
	s_cbranch_scc1 .LBB0_1269
	s_mov_b64 s[0:1], 0

.LBB0_1276:
	v_add_u32_e32 v165, 0, v162
	v_mov_b32_e32 v167, v130
	v_mov_b32_e32 v166, v132
	ds_read_b128 v[98:101], v165
	ds_read_b128 v[102:105], v165 offset:64
	ds_read_b128 v[106:109], v165 offset:128
	ds_read_b128 v[110:113], v165 offset:192
	ds_read_b128 v[114:117], v165 offset:4352
	ds_read_b128 v[118:121], v165 offset:4416
	ds_read_b128 v[122:125], v165 offset:4480
	ds_read_b128 v[126:129], v165 offset:4544
	s_waitcnt vmcnt(3) lgkmcnt(7)
	v_mfma_f32_16x16x32_bf16 v[130:133], v[98:101], v[14:17], 0
	v_cmp_le_i32_e32 vcc, v161, v148
	v_add_u32_e32 v181, 49, v161
	v_add_u32_e32 v182, 50, v161
	v_mfma_f32_16x16x32_bf16 v[98:101], v[98:101], v[18:21], 0
	v_add_u32_e32 v183, 51, v161
	v_cmp_le_i32_e64 s[70:71], v161, v146
	v_add_u32_e32 v164, -1, v164
	s_waitcnt lgkmcnt(6)
	v_mfma_f32_16x16x32_bf16 v[130:133], v[102:105], v[2:5], v[130:133]
	v_add_u32_e32 v162, 0x4400, v162
	s_waitcnt vmcnt(2)
	v_mfma_f32_16x16x32_bf16 v[98:101], v[102:105], v[22:25], v[98:101]
	s_waitcnt lgkmcnt(5)
	v_mfma_f32_16x16x32_bf16 v[102:105], v[106:109], v[6:9], v[130:133]
	s_waitcnt lgkmcnt(4)
	v_mfma_f32_16x16x32_bf16 v[134:137], v[110:113], v[10:13], v[102:105]
	s_waitcnt lgkmcnt(3)
	v_mfma_f32_16x16x32_bf16 v[102:105], v[114:117], v[14:17], 0
	v_mfma_f32_16x16x32_bf16 v[114:117], v[114:117], v[18:21], 0
	s_nop 4
	v_cndmask_b32_e32 v134, v239, v134, vcc
	v_cmp_lt_i32_e32 vcc, v161, v148
	v_cmp_lt_f32_e64 s[4:5], s12, v134
	s_waitcnt lgkmcnt(2)
	v_mfma_f32_16x16x32_bf16 v[102:105], v[118:121], v[2:5], v[102:105]
	v_cndmask_b32_e32 v135, v239, v135, vcc
	v_cmp_lt_f32_e64 s[0:1], s12, v135
	v_mfma_f32_16x16x32_bf16 v[114:117], v[118:121], v[22:25], v[114:117]
	s_waitcnt vmcnt(1)
	v_mfma_f32_16x16x32_bf16 v[98:101], v[106:109], v[26:29], v[98:101]
	s_waitcnt lgkmcnt(1)
	v_mfma_f32_16x16x32_bf16 v[102:105], v[122:125], v[6:9], v[102:105]
	v_mfma_f32_16x16x32_bf16 v[114:117], v[122:125], v[26:29], v[114:117]
	s_waitcnt vmcnt(0)
	v_mfma_f32_16x16x32_bf16 v[98:101], v[110:113], v[30:33], v[98:101]
	ds_read_b128 v[106:109], v165 offset:8704
	ds_read_b128 v[110:113], v165 offset:8768
	ds_read_b128 v[168:171], v165 offset:8832
	ds_read_b128 v[172:175], v165 offset:8896
	s_waitcnt lgkmcnt(4)
	v_mfma_f32_16x16x32_bf16 v[130:133], v[126:129], v[10:13], v[102:105]
	v_mfma_f32_16x16x32_bf16 v[102:105], v[126:129], v[30:33], v[114:117]
	s_nop 2
	ds_read_b128 v[114:117], v165 offset:13056
	ds_read_b128 v[118:121], v165 offset:13120
	ds_read_b128 v[122:125], v165 offset:13184
	ds_read_b128 v[176:179], v165 offset:13248
	v_add_u32_e32 v165, 0, v163
	v_add_u32_e32 v163, 0x80, v163
	s_waitcnt lgkmcnt(7)
	v_mfma_f32_16x16x32_bf16 v[126:129], v[106:109], v[14:17], 0
	v_mfma_f32_16x16x32_bf16 v[106:109], v[106:109], v[18:21], 0
	s_waitcnt lgkmcnt(6)
	v_mfma_f32_16x16x32_bf16 v[126:129], v[110:113], v[2:5], v[126:129]
	v_mfma_f32_16x16x32_bf16 v[106:109], v[110:113], v[22:25], v[106:109]
	s_waitcnt lgkmcnt(5)
	v_mfma_f32_16x16x32_bf16 v[110:113], v[168:171], v[6:9], v[126:129]
	v_mfma_f32_16x16x32_bf16 v[106:109], v[168:171], v[26:29], v[106:109]
	v_add_u32_e32 v169, 2, v161
	v_cmp_le_i32_e32 vcc, v169, v148
	v_add_u32_e32 v170, 3, v161
	s_waitcnt lgkmcnt(4)
	v_mfma_f32_16x16x32_bf16 v[126:129], v[172:175], v[10:13], v[110:113]
	v_cndmask_b32_e32 v136, v239, v136, vcc
	v_cmp_le_i32_e32 vcc, v170, v148
	v_add_u32_e32 v171, 16, v161
	v_mfma_f32_16x16x32_bf16 v[110:113], v[172:175], v[30:33], v[106:109]
	v_cndmask_b32_e32 v137, v239, v137, vcc
	v_cmp_le_i32_e32 vcc, v171, v148
	v_add_u32_e32 v173, 17, v161
	s_waitcnt lgkmcnt(3)
	v_mfma_f32_16x16x32_bf16 v[106:109], v[114:117], v[14:17], 0
	v_max3_f32 v168, v134, s33, v135
	v_cndmask_b32_e32 v172, v239, v130, vcc
	v_cmp_le_i32_e32 vcc, v173, v148
	v_mfma_f32_16x16x32_bf16 v[114:117], v[114:117], v[18:21], 0
	v_max3_f32 v168, v168, v136, v137
	v_cndmask_b32_e32 v131, v239, v131, vcc
	v_max3_f32 v130, v168, v172, v131
	s_waitcnt lgkmcnt(2)
	v_mfma_f32_16x16x32_bf16 v[106:109], v[118:121], v[2:5], v[106:109]
	v_add_u32_e32 v168, 18, v161
	v_cmp_le_i32_e32 vcc, v168, v148
	v_add_u32_e32 v174, 19, v161
	v_mfma_f32_16x16x32_bf16 v[114:117], v[118:121], v[22:25], v[114:117]
	v_cndmask_b32_e32 v132, v239, v132, vcc
	v_cmp_le_i32_e32 vcc, v174, v148
	v_add_u32_e32 v175, 32, v161
	s_waitcnt lgkmcnt(1)
	v_mfma_f32_16x16x32_bf16 v[106:109], v[122:125], v[6:9], v[106:109]
	v_cndmask_b32_e32 v133, v239, v133, vcc
	v_cmp_le_i32_e32 vcc, v175, v148
	v_max3_f32 v130, v130, v132, v133
	v_mfma_f32_16x16x32_bf16 v[114:117], v[122:125], v[26:29], v[114:117]
	v_cndmask_b32_e32 v126, v239, v126, vcc
	v_cmp_lt_f32_e64 s[46:47], s12, v137
	v_cmp_lt_f32_e64 s[52:53], s12, v132
	s_waitcnt lgkmcnt(0)
	v_mfma_f32_16x16x32_bf16 v[122:125], v[176:179], v[10:13], v[106:109]
	v_cmp_lt_f32_e64 s[50:51], s12, v131
	v_cmp_lt_f32_e64 s[48:49], s12, v172
	v_cmp_lt_f32_e64 s[54:55], s12, v126
	v_mfma_f32_16x16x32_bf16 v[106:109], v[176:179], v[30:33], v[114:117]
	v_add_u32_e32 v176, 33, v161
	v_cmp_le_i32_e32 vcc, v176, v148
	v_add_u32_e32 v177, 34, v161
	v_add_u32_e32 v178, 35, v161
	v_cndmask_b32_e32 v127, v239, v127, vcc
	v_cmp_le_i32_e32 vcc, v177, v148
	v_add_u32_e32 v179, 48, v161
	v_max3_f32 v130, v130, v126, v127
	v_cndmask_b32_e32 v128, v239, v128, vcc
	v_cmp_le_i32_e32 vcc, v178, v148
	v_add_u32_e32 v114, 0x11800, v165
	v_add_u32_e32 v116, 0x11820, v165
	v_cndmask_b32_e32 v129, v239, v129, vcc
	v_cmp_le_i32_e32 vcc, v179, v148
	v_max3_f32 v130, v130, v128, v129
	v_add_u32_e32 v118, 0x11840, v165
	v_cndmask_b32_e32 v180, v239, v122, vcc
	v_cmp_le_i32_e32 vcc, v181, v148
	v_add_u32_e32 v120, 0x11860, v165
	ds_read_b64 v[114:115], v114
	ds_read_b64 v[116:117], v116
	ds_read_b64 v[118:119], v118
	ds_read_b64 v[120:121], v120
	v_cndmask_b32_e32 v123, v239, v123, vcc
	v_cmp_le_i32_e32 vcc, v182, v148
	v_max3_f32 v122, v130, v180, v123
	v_cmp_lt_f32_e64 s[64:65], s12, v123
	v_cndmask_b32_e32 v124, v239, v124, vcc
	v_cmp_le_i32_e32 vcc, v183, v148
	v_cmp_lt_f32_e64 s[66:67], s12, v124
	v_cmp_lt_f32_e64 s[56:57], s12, v127
	v_cndmask_b32_e32 v125, v239, v125, vcc
	v_max3_f32 v122, v122, v124, v125
	v_mov_b32_e32 v130, v122
	v_mov_b32_e32 v159, v122
	s_nop 1
	v_permlane16_swap_b32_e32 v130, v159
	v_cmp_lt_f32_e64 s[68:69], s12, v125
	v_cmp_lt_f32_e64 s[58:59], s12, v128
	v_cmp_lt_f32_e64 s[60:61], s12, v129
	v_cmp_lt_f32_e64 s[62:63], s12, v180
	s_waitcnt lgkmcnt(0)
	v_max_f32_e32 v122, v130, v159
	v_mov_b32_e32 v130, v122
	v_mov_b32_e32 v159, v122
	s_nop 1
	v_permlane32_swap_b32_e32 v130, v159
	v_cmp_lt_f32_e64 s[44:45], s12, v136
	s_waitcnt lgkmcnt(0)
	v_max3_f32 v130, v167, v130, v159
	v_sub_f32_e32 v122, v134, v130
	v_exp_f32_e32 v184, v122
	v_sub_f32_e32 v122, v135, v130
	v_exp_f32_e32 v185, v122
	v_sub_f32_e32 v122, v136, v130
	v_exp_f32_e32 v135, v122
	v_sub_f32_e32 v122, v137, v130
	v_exp_f32_e32 v186, v122
	v_sub_f32_e32 v122, v172, v130
	v_exp_f32_e32 v137, v122
	v_sub_f32_e32 v122, v131, v130
	v_exp_f32_e32 v187, v122
	v_sub_f32_e32 v122, v132, v130
	v_exp_f32_e32 v122, v122
	v_sub_f32_e32 v167, v167, v130
	v_sub_f32_e32 v131, v133, v130
	v_sub_f32_e32 v132, v126, v130
	v_cndmask_b32_e64 v122, 0, v122, s[52:53]
	v_cmp_lt_f32_e64 s[52:53], s12, v133
	v_sub_f32_e32 v133, v123, v130
	v_sub_f32_e32 v123, v124, v130
	v_sub_f32_e32 v124, v125, v130
	v_exp_f32_e32 v172, v124
	v_exp_f32_e32 v124, v167
	v_exp_f32_e32 v132, v132
	v_exp_f32_e32 v131, v131
	v_exp_f32_e32 v123, v123
	v_pk_mul_f32 v[60:61], v[60:61], v[124:125] op_sel_hi:[1,0]
	v_pk_mul_f32 v[58:59], v[58:59], v[124:125] op_sel_hi:[1,0]
	v_pk_mul_f32 v[64:65], v[64:65], v[124:125] op_sel_hi:[1,0]
	v_pk_mul_f32 v[62:63], v[62:63], v[124:125] op_sel_hi:[1,0]
	v_pk_mul_f32 v[68:69], v[68:69], v[124:125] op_sel_hi:[1,0]
	v_pk_mul_f32 v[66:67], v[66:67], v[124:125] op_sel_hi:[1,0]
	v_pk_mul_f32 v[72:73], v[72:73], v[124:125] op_sel_hi:[1,0]
	v_pk_mul_f32 v[70:71], v[70:71], v[124:125] op_sel_hi:[1,0]
	v_pk_mul_f32 v[76:77], v[76:77], v[124:125] op_sel_hi:[1,0]
	v_pk_mul_f32 v[74:75], v[74:75], v[124:125] op_sel_hi:[1,0]
	v_pk_mul_f32 v[80:81], v[80:81], v[124:125] op_sel_hi:[1,0]
	v_pk_mul_f32 v[78:79], v[78:79], v[124:125] op_sel_hi:[1,0]
	v_pk_mul_f32 v[92:93], v[92:93], v[124:125] op_sel_hi:[1,0]
	v_pk_mul_f32 v[90:91], v[90:91], v[124:125] op_sel_hi:[1,0]
	v_pk_mul_f32 v[96:97], v[96:97], v[124:125] op_sel_hi:[1,0]
	v_pk_mul_f32 v[94:95], v[94:95], v[124:125] op_sel_hi:[1,0]
	v_cndmask_b32_e64 v125, v239, v98, s[70:71]
	v_cmp_lt_i32_e64 s[70:71], v161, v146
	v_sub_f32_e32 v126, v127, v130
	v_sub_f32_e32 v127, v128, v130
	v_cndmask_b32_e64 v188, v239, v99, s[70:71]
	v_cmp_le_i32_e64 s[70:71], v169, v146
	v_max3_f32 v98, v125, s33, v188
	v_cmp_lt_f32_e64 s[74:75], s12, v188
	v_cndmask_b32_e64 v169, v239, v100, s[70:71]
	v_cmp_le_i32_e64 s[70:71], v170, v146
	v_cndmask_b32_e64 v170, 0, v172, s[68:69]
	v_cndmask_b32_e64 v172, 0, v185, s[0:1]
	v_cndmask_b32_e64 v189, v239, v101, s[70:71]
	v_cmp_le_i32_e64 s[70:71], v171, v146
	v_max3_f32 v98, v98, v169, v189
	v_cmp_lt_f32_e64 s[76:77], s12, v169
	v_cndmask_b32_e64 v171, v239, v102, s[70:71]
	v_cmp_le_i32_e64 s[70:71], v173, v146
	v_cmp_lt_f32_e64 s[78:79], s12, v189
	v_cmp_lt_f32_e64 s[80:81], s12, v171
	v_cndmask_b32_e64 v190, v239, v103, s[70:71]
	v_cmp_le_i32_e64 s[70:71], v168, v146
	v_max3_f32 v98, v98, v171, v190
	v_cmp_lt_f32_e64 s[82:83], s12, v190
	v_cndmask_b32_e64 v191, v239, v104, s[70:71]
	v_cmp_le_i32_e64 s[70:71], v174, v146
	v_cmp_lt_f32_e64 s[84:85], s12, v191
	v_cndmask_b32_e64 v168, 0, v123, s[66:67]
	v_cndmask_b32_e64 v192, v239, v105, s[70:71]
	v_cmp_le_i32_e64 s[70:71], v175, v146
	v_max3_f32 v98, v98, v191, v192
	v_cmp_lt_f32_e64 s[86:87], s12, v192
	v_cndmask_b32_e64 v193, v239, v110, s[70:71]
	v_cmp_le_i32_e64 s[70:71], v176, v146
	v_cndmask_b32_e64 v110, 0, v132, s[54:55]
	v_cmp_lt_f32_e64 s[88:89], s12, v193
	v_cndmask_b32_e64 v194, v239, v111, s[70:71]
	v_cmp_le_i32_e64 s[70:71], v177, v146
	v_max3_f32 v98, v98, v193, v194
	v_cmp_lt_f32_e64 s[90:91], s12, v194
	v_cndmask_b32_e64 v195, v239, v112, s[70:71]
	v_cmp_le_i32_e64 s[70:71], v178, v146
	v_exp_f32_e32 v126, v126
	v_exp_f32_e32 v127, v127
	v_cndmask_b32_e64 v196, v239, v113, s[70:71]
	v_cmp_le_i32_e64 s[70:71], v179, v146
	v_max3_f32 v98, v98, v195, v196
	v_cmp_lt_f32_e64 s[92:93], s12, v195
	v_cndmask_b32_e64 v197, v239, v106, s[70:71]
	v_cmp_le_i32_e64 s[70:71], v181, v146
	v_cndmask_b32_e64 v106, 0, v184, s[4:5]
	v_cvt_pk_bf16_f32 v102, v106, v172
	v_sub_f32_e32 v128, v129, v130
	v_cndmask_b32_e64 v198, v239, v107, s[70:71]
	v_cmp_le_i32_e64 s[70:71], v182, v146
	v_max3_f32 v98, v98, v197, v198
	v_sub_f32_e32 v129, v180, v130
	v_cndmask_b32_e64 v182, v239, v108, s[70:71]
	v_cmp_le_i32_e64 s[70:71], v183, v146
	v_cndmask_b32_e64 v108, 0, v131, s[52:53]
	v_cndmask_b32_e64 v112, 0, v126, s[56:57]
	v_cndmask_b32_e64 v183, v239, v109, s[70:71]
	v_max3_f32 v107, v98, v182, v183
	v_mov_b32_e32 v109, v107
	v_mov_b32_e32 v159, v107
	s_nop 1
	v_permlane16_swap_b32_e32 v109, v159
	v_cmp_lt_f32_e64 s[70:71], s12, v125
	v_cndmask_b32_e64 v126, 0, v127, s[58:59]
	v_exp_f32_e32 v129, v129
	v_cmp_lt_f32_e64 s[94:95], s12, v196
	s_waitcnt lgkmcnt(0)
	v_max_f32_e32 v107, v109, v159
	v_mov_b32_e32 v109, v107
	v_mov_b32_e32 v159, v107
	s_nop 1
	v_permlane32_swap_b32_e32 v109, v159
	v_cndmask_b32_e64 v134, 0, v129, s[62:63]
	v_cmp_lt_f32_e64 s[96:97], s12, v197
	v_cndmask_b32_e64 v174, 0, v135, s[44:45]
	v_cndmask_b32_e64 v176, 0, v186, s[46:47]
	s_waitcnt lgkmcnt(0)
	v_max3_f32 v132, v166, v109, v159
	v_sub_f32_e32 v107, v125, v132
	v_exp_f32_e32 v107, v107
	v_sub_f32_e32 v131, v166, v132
	v_cmp_lt_f32_e32 vcc, s12, v198
	v_cndmask_b32_e64 v178, 0, v137, s[48:49]
	v_cndmask_b32_e64 v107, 0, v107, s[70:71]
	v_pk_add_f32 v[166:167], v[106:107], 0 op_sel_hi:[1,0]
	v_sub_f32_e32 v106, v188, v132
	v_exp_f32_e32 v106, v106
	v_cndmask_b32_e64 v180, 0, v187, s[50:51]
	v_exp_f32_e32 v128, v128
	v_exp_f32_e32 v133, v133
	v_cndmask_b32_e64 v173, 0, v106, s[74:75]
	v_sub_f32_e32 v106, v169, v132
	v_exp_f32_e32 v106, v106
	v_pk_add_f32 v[166:167], v[172:173], v[166:167]
	v_cmp_lt_f32_e64 s[6:7], s12, v182
	v_cndmask_b32_e64 v128, 0, v128, s[60:61]
	v_cndmask_b32_e64 v175, 0, v106, s[76:77]
	v_sub_f32_e32 v106, v189, v132
	v_exp_f32_e32 v106, v106
	v_pk_add_f32 v[166:167], v[174:175], v[166:167]
	v_cndmask_b32_e64 v136, 0, v133, s[64:65]
	v_exp_f32_e32 v125, v131
	v_cndmask_b32_e64 v177, 0, v106, s[78:79]
	v_sub_f32_e32 v106, v171, v132
	v_exp_f32_e32 v106, v106
	v_pk_add_f32 v[166:167], v[176:177], v[166:167]
	v_cmp_lt_f32_e64 s[8:9], s12, v183
	v_cvt_pk_bf16_f32 v103, v174, v176
	v_cndmask_b32_e64 v179, 0, v106, s[80:81]
	v_sub_f32_e32 v106, v190, v132
	v_exp_f32_e32 v106, v106
	v_pk_add_f32 v[166:167], v[178:179], v[166:167]
	v_cvt_pk_bf16_f32 v104, v178, v180
	v_cvt_pk_bf16_f32 v105, v122, v108
	v_cndmask_b32_e64 v181, 0, v106, s[82:83]
	v_sub_f32_e32 v106, v191, v132
	v_exp_f32_e32 v106, v106
	v_pk_add_f32 v[166:167], v[180:181], v[166:167]
	v_cvt_pk_bf16_f32 v98, v110, v112
	v_cvt_pk_bf16_f32 v99, v126, v128
	v_cndmask_b32_e64 v123, 0, v106, s[84:85]
	v_sub_f32_e32 v106, v192, v132
	v_exp_f32_e32 v106, v106
	v_pk_add_f32 v[166:167], v[122:123], v[166:167]
	v_add_u32_e32 v122, 0x13900, v165
	v_cvt_pk_bf16_f32 v100, v134, v136
	v_cndmask_b32_e64 v109, 0, v106, s[86:87]
	v_sub_f32_e32 v106, v193, v132
	v_exp_f32_e32 v106, v106
	v_pk_add_f32 v[166:167], v[108:109], v[166:167]
	v_cvt_pk_bf16_f32 v101, v168, v170
	v_mfma_f32_16x16x32_bf16 v[58:61], v[114:117], v[102:105], v[58:61]
	v_cndmask_b32_e64 v111, 0, v106, s[88:89]
	v_sub_f32_e32 v106, v194, v132
	v_exp_f32_e32 v106, v106
	v_pk_add_f32 v[166:167], v[110:111], v[166:167]
	v_mfma_f32_16x16x32_bf16 v[58:61], v[118:121], v[98:101], v[58:61]
	v_add_u32_e32 v161, 64, v161
	v_cndmask_b32_e64 v113, 0, v106, s[90:91]
	v_sub_f32_e32 v106, v195, v132
	v_exp_f32_e32 v106, v106
	v_pk_add_f32 v[166:167], v[112:113], v[166:167]
	v_cndmask_b32_e64 v127, 0, v106, s[92:93]
	v_sub_f32_e32 v106, v196, v132
	v_exp_f32_e32 v106, v106
	v_pk_add_f32 v[166:167], v[126:127], v[166:167]
	v_add_u32_e32 v126, 0x13940, v165
	v_cndmask_b32_e64 v129, 0, v106, s[94:95]
	v_sub_f32_e32 v106, v197, v132
	v_exp_f32_e32 v106, v106
	v_pk_add_f32 v[166:167], v[128:129], v[166:167]
	v_add_u32_e32 v128, 0x13960, v165
	v_cndmask_b32_e64 v135, 0, v106, s[96:97]
	v_sub_f32_e32 v106, v198, v132
	v_exp_f32_e32 v106, v106
	v_pk_add_f32 v[166:167], v[134:135], v[166:167]
	v_cndmask_b32_e32 v137, 0, v106, vcc
	v_sub_f32_e32 v106, v182, v132
	v_exp_f32_e32 v106, v106
	v_pk_add_f32 v[166:167], v[136:137], v[166:167]
	v_cmp_eq_u32_e32 vcc, 0, v164
	s_or_b64 s[2:3], vcc, s[2:3]
	v_cndmask_b32_e64 v169, 0, v106, s[6:7]
	v_sub_f32_e32 v106, v183, v132
	v_exp_f32_e32 v106, v106
	v_pk_add_f32 v[166:167], v[168:169], v[166:167]
	v_cndmask_b32_e64 v171, 0, v106, s[8:9]
	v_pk_add_f32 v[166:167], v[170:171], v[166:167]
	v_mov_b32_e32 v106, v125
	v_pk_fma_f32 v[150:151], v[150:151], v[124:125], v[166:167]
	v_add_u32_e32 v124, 0x13920, v165
	v_pk_mul_f32 v[36:37], v[36:37], v[106:107] op_sel_hi:[1,0]
	v_pk_mul_f32 v[34:35], v[34:35], v[106:107] op_sel_hi:[1,0]
	v_pk_mul_f32 v[40:41], v[40:41], v[106:107] op_sel_hi:[1,0]
	v_pk_mul_f32 v[38:39], v[38:39], v[106:107] op_sel_hi:[1,0]
	v_pk_mul_f32 v[44:45], v[44:45], v[106:107] op_sel_hi:[1,0]
	v_pk_mul_f32 v[42:43], v[42:43], v[106:107] op_sel_hi:[1,0]
	v_pk_mul_f32 v[48:49], v[48:49], v[106:107] op_sel_hi:[1,0]
	v_pk_mul_f32 v[46:47], v[46:47], v[106:107] op_sel_hi:[1,0]
	v_pk_mul_f32 v[52:53], v[52:53], v[106:107] op_sel_hi:[1,0]
	v_pk_mul_f32 v[50:51], v[50:51], v[106:107] op_sel_hi:[1,0]
	v_pk_mul_f32 v[56:57], v[56:57], v[106:107] op_sel_hi:[1,0]
	v_pk_mul_f32 v[54:55], v[54:55], v[106:107] op_sel_hi:[1,0]
	v_pk_mul_f32 v[88:89], v[88:89], v[106:107] op_sel_hi:[1,0]
	v_pk_mul_f32 v[86:87], v[86:87], v[106:107] op_sel_hi:[1,0]
	v_pk_mul_f32 v[84:85], v[84:85], v[106:107] op_sel_hi:[1,0]
	v_pk_mul_f32 v[82:83], v[82:83], v[106:107] op_sel_hi:[1,0]
	v_cvt_pk_bf16_f32 v106, v107, v173
	v_cvt_pk_bf16_f32 v107, v175, v177
	v_cvt_pk_bf16_f32 v108, v179, v181
	v_cvt_pk_bf16_f32 v109, v123, v109
	v_cvt_pk_bf16_f32 v110, v111, v113
	v_cvt_pk_bf16_f32 v111, v127, v129
	v_cvt_pk_bf16_f32 v112, v135, v137
	v_cvt_pk_bf16_f32 v113, v169, v171
	ds_read_b64 v[122:123], v122
	ds_read_b64 v[124:125], v124
	ds_read_b64 v[126:127], v126
	ds_read_b64 v[128:129], v128
	v_mfma_f32_16x16x32_bf16 v[34:37], v[114:117], v[106:109], v[34:37]
	v_add_u32_e32 v114, 0x15a00, v165
	v_add_u32_e32 v116, 0x15a20, v165
	ds_read_b64 v[114:115], v114
	ds_read_b64 v[116:117], v116
	s_waitcnt lgkmcnt(4)
	v_mfma_f32_16x16x32_bf16 v[62:65], v[122:125], v[102:105], v[62:65]
	v_mfma_f32_16x16x32_bf16 v[38:41], v[122:125], v[106:109], v[38:41]
	v_add_u32_e32 v122, 0x17b00, v165
	v_add_u32_e32 v124, 0x17b20, v165
	ds_read_b64 v[122:123], v122
	ds_read_b64 v[124:125], v124
	v_mfma_f32_16x16x32_bf16 v[34:37], v[118:121], v[110:113], v[34:37]
	v_add_u32_e32 v118, 0x15a40, v165
	v_add_u32_e32 v120, 0x15a60, v165
	ds_read_b64 v[118:119], v118
	ds_read_b64 v[120:121], v120
	s_waitcnt lgkmcnt(6)
	v_mfma_f32_16x16x32_bf16 v[62:65], v[126:129], v[98:101], v[62:65]
	v_mfma_f32_16x16x32_bf16 v[38:41], v[126:129], v[110:113], v[38:41]
	v_add_u32_e32 v126, 0x17b40, v165
	v_add_u32_e32 v128, 0x17b60, v165
	ds_read_b64 v[126:127], v126
	ds_read_b64 v[128:129], v128
	s_waitcnt lgkmcnt(6)
	v_mfma_f32_16x16x32_bf16 v[66:69], v[114:117], v[102:105], v[66:69]
	v_mfma_f32_16x16x32_bf16 v[42:45], v[114:117], v[106:109], v[42:45]
	v_add_u32_e32 v114, 0x19c00, v165
	v_add_u32_e32 v116, 0x19c20, v165
	ds_read_b64 v[114:115], v114
	ds_read_b64 v[116:117], v116
	s_waitcnt lgkmcnt(6)
	v_mfma_f32_16x16x32_bf16 v[70:73], v[122:125], v[102:105], v[70:73]
	v_mfma_f32_16x16x32_bf16 v[46:49], v[122:125], v[106:109], v[46:49]
	v_add_u32_e32 v122, 0x1bd00, v165
	v_add_u32_e32 v124, 0x1bd20, v165
	ds_read_b64 v[122:123], v122
	ds_read_b64 v[124:125], v124
	s_waitcnt lgkmcnt(6)
	v_mfma_f32_16x16x32_bf16 v[66:69], v[118:121], v[98:101], v[66:69]
	v_mfma_f32_16x16x32_bf16 v[42:45], v[118:121], v[110:113], v[42:45]
	v_add_u32_e32 v118, 0x19c40, v165
	v_add_u32_e32 v120, 0x19c60, v165
	ds_read_b64 v[118:119], v118
	ds_read_b64 v[120:121], v120
	s_waitcnt lgkmcnt(6)
	v_mfma_f32_16x16x32_bf16 v[70:73], v[126:129], v[98:101], v[70:73]
	v_mfma_f32_16x16x32_bf16 v[46:49], v[126:129], v[110:113], v[46:49]
	v_add_u32_e32 v126, 0x1bd40, v165
	v_add_u32_e32 v128, 0x1bd60, v165
	ds_read_b64 v[126:127], v126
	ds_read_b64 v[128:129], v128
	s_waitcnt lgkmcnt(6)
	v_mfma_f32_16x16x32_bf16 v[74:77], v[114:117], v[102:105], v[74:77]
	v_mfma_f32_16x16x32_bf16 v[50:53], v[114:117], v[106:109], v[50:53]
	v_add_u32_e32 v114, 0x1de00, v165
	v_add_u32_e32 v116, 0x1de20, v165
	ds_read_b64 v[114:115], v114
	ds_read_b64 v[116:117], v116
	s_waitcnt lgkmcnt(6)
	v_mfma_f32_16x16x32_bf16 v[78:81], v[122:125], v[102:105], v[78:81]
	v_mfma_f32_16x16x32_bf16 v[54:57], v[122:125], v[106:109], v[54:57]
	v_add_u32_e32 v122, 0x1ff00, v165
	v_add_u32_e32 v124, 0x1ff20, v165
	ds_read_b64 v[122:123], v122
	ds_read_b64 v[124:125], v124
	s_waitcnt lgkmcnt(6)
	v_mfma_f32_16x16x32_bf16 v[74:77], v[118:121], v[98:101], v[74:77]
	v_mfma_f32_16x16x32_bf16 v[50:53], v[118:121], v[110:113], v[50:53]
	v_add_u32_e32 v118, 0x1de40, v165
	v_add_u32_e32 v120, 0x1de60, v165
	ds_read_b64 v[118:119], v118
	ds_read_b64 v[120:121], v120
	s_waitcnt lgkmcnt(6)
	v_mfma_f32_16x16x32_bf16 v[78:81], v[126:129], v[98:101], v[78:81]
	v_mfma_f32_16x16x32_bf16 v[54:57], v[126:129], v[110:113], v[54:57]
	v_add_u32_e32 v126, 0x1ff40, v165
	v_add_u32_e32 v128, 0x1ff60, v165
	ds_read_b64 v[126:127], v126
	ds_read_b64 v[128:129], v128
	s_waitcnt lgkmcnt(6)
	v_mfma_f32_16x16x32_bf16 v[90:93], v[114:117], v[102:105], v[90:93]
	v_mfma_f32_16x16x32_bf16 v[86:89], v[114:117], v[106:109], v[86:89]
	s_waitcnt lgkmcnt(4)
	v_mfma_f32_16x16x32_bf16 v[94:97], v[122:125], v[102:105], v[94:97]
	v_mfma_f32_16x16x32_bf16 v[82:85], v[122:125], v[106:109], v[82:85]
	s_waitcnt lgkmcnt(2)
	v_mfma_f32_16x16x32_bf16 v[90:93], v[118:121], v[98:101], v[90:93]
	v_mfma_f32_16x16x32_bf16 v[86:89], v[118:121], v[110:113], v[86:89]
	s_waitcnt lgkmcnt(0)
	v_mfma_f32_16x16x32_bf16 v[94:97], v[126:129], v[98:101], v[94:97]
	v_mfma_f32_16x16x32_bf16 v[82:85], v[126:129], v[110:113], v[82:85]
	s_andn2_b64 exec, exec, s[2:3]
	s_cbranch_execnz .LBB0_1276
	s_or_b64 exec, exec, s[2:3]
	v_readlane_b32 s88, v254, 54
	v_readlane_b32 s86, v254, 62
	v_readlane_b32 s84, v254, 52
	v_readlane_b32 s48, v255, 10
	v_readlane_b32 s50, v255, 12
	v_mov_b32_e32 v131, v226
	v_mov_b32_e32 v134, v232
	v_mov_b32_e32 v133, v227
	v_mov_b32_e32 v135, v233
	v_readlane_b32 s89, v254, 55
	v_readlane_b32 s90, v254, 56
	v_readlane_b32 s91, v254, 57
	v_readlane_b32 s92, v254, 58
	v_readlane_b32 s93, v254, 59
	v_readlane_b32 s94, v254, 60
	v_readlane_b32 s95, v254, 61
	v_readlane_b32 s87, v254, 63
	s_mov_b32 s96, s24
	s_movk_i32 s97, 0xa1
	v_readlane_b32 s85, v254, 53
	s_mov_b32 s67, 0x800000
	s_movk_i32 s63, 0x5000
	s_mov_b32 s56, 0x19ca0000
	s_movk_i32 s57, 0x210
	v_readlane_b32 s46, v255, 8
	v_readlane_b32 s49, v255, 11
	v_readlane_b32 s51, v255, 13
	v_readlane_b32 s47, v255, 9
